# indexer radix passes 1-3 on top of the scan-zeroing version: four keys tested per branch (xor with shifted prefix, min3/min, one compare), v_bfe + cndmask bin on the matching path
# baseline (speedup 1.0000x reference)
; #define SEL_HADD(idx_) __hip_atomic_fetch_add(&hist[(idx_)], 1u, __ATOMIC_RELAXED, __HIP_MEMORY_SCOPE_WORKGROUP)
; __device__ __forceinline__ void sel_unit(LAS char* lds, int b, int u, const bf16_t* QI, const bf16_t* KIDX, const float* WIDX, unsigned long long* MASK) {
;     ...
;         const unsigned pf = pref[q16];
;         unsigned zz = 0u; asm volatile("" : "+v"(zz));
; #pragma unroll
;         for (int j = 0; j < 8; ++j) if (j < nj) {
; #pragma unroll
;             for (int kb = 0; kb < 4; ++kb)
; #pragma unroll
;                 for (int i = 0; i < 4; ++i) { const unsigned k = sc[j][kb][i] | zz; SEL_HADD((((k >> (shift + 8)) == pf) ? ((k >> shift) & 255u) * 16 : 4096u) + q16); __builtin_amdgcn_sched_barrier(0); }
;         }
.LBB0_706:
	ds_read_b32 v2, v60 offset:34880
	s_lshl_b32 s2, s21, 3
	s_sub_i32 s16, 24, s2
	v_mov_b32_e32 v3, 0
	s_sub_i32 s17, 32, s2
	s_waitcnt lgkmcnt(0)
	v_lshlrev_b32_e32 v34, s17, v2
	v_mov_b32_e32 v35, 0x100
	s_lshl_b32 s76, 1, s17
	s_and_b64 vcc, exec, s[22:23]
	s_cbranch_vccz .LBB0_711
	v_xor_b32_e32 v36, v34, v62
	v_xor_b32_e32 v37, v34, v61
	v_xor_b32_e32 v38, v34, v64
	v_xor_b32_e32 v39, v34, v63
	v_min3_u32 v40, v36, v37, v38
	v_min_u32_e32 v40, v40, v39
	v_cmp_gt_u32_e32 vcc, s76, v40
	s_cbranch_vccz .Lsel_grp_1
	v_cmp_gt_u32_e32 vcc, s76, v36
	v_cmp_gt_u32_e64 s[28:29], s76, v37
	v_cmp_gt_u32_e64 s[44:45], s76, v38
	v_cmp_gt_u32_e64 s[74:75], s76, v39
	v_bfe_u32 v36, v62, s16, 8
	v_bfe_u32 v37, v61, s16, 8
	v_bfe_u32 v38, v64, s16, 8
	v_bfe_u32 v39, v63, s16, 8
	v_cndmask_b32_e32 v36, v35, v36, vcc
	v_cndmask_b32_e64 v37, v35, v37, s[28:29]
	v_cndmask_b32_e64 v38, v35, v38, s[44:45]
	v_cndmask_b32_e64 v39, v35, v39, s[74:75]
	v_lshl_add_u32 v36, v36, 6, v0
	v_lshl_add_u32 v37, v37, 6, v0
	v_lshl_add_u32 v38, v38, 6, v0
	v_lshl_add_u32 v39, v39, 6, v0
	ds_add_u32 v36, v205 offset:16384
	ds_add_u32 v37, v205 offset:16384
	ds_add_u32 v38, v205 offset:16384
	ds_add_u32 v39, v205 offset:16384
